# scan tail: removed the lgkmcnt(0) between the wave's own y-partial ds_writes and its trip-end ds_reads (same-wave LDS ops are in order)
# speedup vs baseline: 1.0960x; 1.0027x over previous
; __device__ __forceinline__ unsigned pack2(float lo, float hi) { return (unsigned)f2bf(lo) | ((unsigned)f2bf(hi) << 16); }
; __device__ void phase_scan(int c, const bf16_t* PROJ, const float* k_k, const bf16_t* Wd, const bf16_t* Bd, const float* k_a, bf16_t* Y, bf16_t* Q, float* FS, float* sm) {
;     ...
;                 __builtin_amdgcn_wave_barrier(); asm volatile("s_waitcnt lgkmcnt(0)" ::: "memory");
;                 { const int st = lane >> 2, v4 = (lane & 3) * 4;
;                   const int g = g0 + ci * 16 + st; const int t = dir ? (L - 1 - g) : g;
;                   const size_t o = ((size_t)dir * TCH + (size_t)seq * L + t) * 512 + h * 64 + wq * 16 + v4;
;                   const f32x4 yv = *(const f32x4*)(obw + st * 16 + v4);
;                   uint2 pk; pk.x = pack2(yv[0], yv[1]); pk.y = pack2(yv[2], yv[3]); *(uint2*)(gout + o) = pk; }
;                 __builtin_amdgcn_wave_barrier();
.Lscan_body_end:
	v_add_u32_e32 v84, s40, v82
	v_cndmask_b32_e64 v88, v83, v84, s[10:11]
	ds_read_b128 v[196:199], v229
	ds_read_b128 v[200:203], v229 offset:64
	ds_read_b128 v[204:207], v231 offset:128
	ds_read_b128 v[208:211], v231 offset:192
	ds_read_b128 v[212:215], v234 offset:256
	ds_read_b128 v[216:219], v234 offset:320
	ds_read_b128 v[220:223], v235 offset:384
	ds_read_b128 v[224:227], v235 offset:448
	v_ashrrev_i32_e32 v89, 31, v88
	v_lshl_add_u64 v[88:89], v[60:61], 0, v[88:89]
	v_lshlrev_b64 v[88:89], 10, v[88:89]
	v_lshl_add_u64 v[88:89], v[62:63], 0, v[88:89]
	s_waitcnt lgkmcnt(0)
	v_pk_add_f32 v[196:197], v[196:197], v[200:201]
	v_pk_add_f32 v[204:205], v[204:205], v[208:209]
	v_pk_add_f32 v[212:213], v[212:213], v[216:217]
	v_pk_add_f32 v[220:221], v[220:221], v[224:225]
	v_pk_add_f32 v[198:199], v[198:199], v[202:203]
	v_pk_add_f32 v[206:207], v[206:207], v[210:211]
	v_pk_add_f32 v[214:215], v[214:215], v[218:219]
	v_pk_add_f32 v[222:223], v[222:223], v[226:227]
	v_pk_add_f32 v[196:197], v[196:197], v[204:205]
	v_pk_add_f32 v[212:213], v[212:213], v[220:221]
	v_pk_add_f32 v[198:199], v[198:199], v[206:207]
	v_pk_add_f32 v[214:215], v[214:215], v[222:223]
	v_pk_add_f32 v[84:85], v[196:197], v[212:213]
	v_pk_add_f32 v[86:87], v[198:199], v[214:215]
	s_nop 0
	v_and_b32_sdwa v90, v86, v185 dst_sel:DWORD dst_unused:UNUSED_PAD src0_sel:WORD_1 src1_sel:DWORD
	v_and_b32_sdwa v91, v84, v185 dst_sel:DWORD dst_unused:UNUSED_PAD src0_sel:WORD_1 src1_sel:DWORD
	v_add3_u32 v84, v84, v91, s46
	v_add3_u32 v86, v86, v90, s46
	v_and_b32_sdwa v90, v87, v185 dst_sel:DWORD dst_unused:UNUSED_PAD src0_sel:WORD_1 src1_sel:DWORD
	v_and_b32_sdwa v91, v85, v185 dst_sel:DWORD dst_unused:UNUSED_PAD src0_sel:WORD_1 src1_sel:DWORD
	v_add3_u32 v87, v87, v90, s46
	v_add3_u32 v85, v85, v91, s46
	v_and_b32_e32 v87, 0xffff0000, v87
	v_and_b32_e32 v90, 0xffff0000, v85
	v_or_b32_sdwa v85, v87, v86 dst_sel:DWORD dst_unused:UNUSED_PAD src0_sel:DWORD src1_sel:WORD_1
	v_or_b32_sdwa v84, v90, v84 dst_sel:DWORD dst_unused:UNUSED_PAD src0_sel:DWORD src1_sel:WORD_1
	global_store_dwordx2 v[88:89], v[84:85], off
	s_branch .LBB0_71
